# GLA scan software pipelining: gate section B1 of step k+1 (MFMA + logsigmoid arithmetic) runs inside section D of step k in the output-MFMA shadows; gates wait in registers and are stored in section A
# baseline (speedup 1.0000x reference)
; __device__ __forceinline__ void scan_unit(const int unit, const Args& a, unsigned char* lds, const int mk_wid) {
;     ...
;     GLA_LOAD(0);
;     ...
;           const bf16x8 af = *(const bf16x8*)(lds + L_LR + (tt * 32 + r32) * 32 + hi * 16);
.Lscan_qk_done2:
	v_mov_b32_e32 v128, 0
	v_mov_b32_e32 v129, 0
	v_mov_b32_e32 v130, 0
	v_mov_b32_e32 v131, 0
	v_mov_b32_e32 v132, 0
	v_mov_b32_e32 v133, 0
	v_mov_b32_e32 v134, 0
	v_mov_b32_e32 v135, 0
	v_mbcnt_lo_u32_b32 v66, -1, 0
	v_mbcnt_hi_u32_b32 v66, -1, v66
	v_bfe_u32 v67, v66, 4, 1
	v_lshlrev_b32_e32 v67, 3, v67
	v_bfe_u32 v68, v66, 2, 2
	v_add_u32_e32 v67, v67, v68
	s_and_b32 s96, s70, 3
	s_lshl_b32 s96, s96, 4
	v_add_u32_e32 v67, s96, v67
	v_lshrrev_b32_e32 v68, 5, v66
	v_lshlrev_b32_e32 v68, 6, v68
	v_and_b32_e32 v69, 3, v66
	v_lshl_add_u32 v68, v69, 4, v68
	s_lshr_b32 s96, s70, 2
	s_lshl_b32 s96, s96, 8
	v_add_u32_e32 v68, s96, v68
	v_sub_u32_e32 v69, 63, v67
	v_cndmask_b32_e64 v69, v69, v67, s[2:3]
	v_add_u32_e32 v69, s12, v69
	v_lshl_add_u32 v247, v69, 11, v68
	v_add_u32_e32 v248, 0x80, v247
	v_add_u32_e32 v67, 4, v67
	v_sub_u32_e32 v69, 63, v67
	v_cndmask_b32_e64 v69, v69, v67, s[2:3]
	v_add_u32_e32 v69, s12, v69
	v_lshl_add_u32 v249, v69, 11, v68
	v_add_u32_e32 v250, 0x80, v249
	v_mbcnt_lo_u32_b32 v66, -1, 0
	v_mbcnt_hi_u32_b32 v66, -1, v66
	s_lshr_b32 s96, s70, 2
	s_lshl_b32 s96, s96, 5
	v_and_b32_e32 v67, 31, v66
	v_add_u32_e32 v67, s96, v67
	v_sub_u32_e32 v68, 63, v67
	v_cndmask_b32_e64 v67, v68, v67, s[2:3]
	v_add_u32_e32 v67, s12, v67
	v_bfe_u32 v68, v66, 5, 1
	v_lshlrev_b32_e32 v68, 4, v68
	v_lshl_add_u32 v251, v67, 6, v68
	s_bitcmp1_b32 s8, 0
	s_cselect_b32 s97, 3, 0
	s_lshl_b32 s97, s97, 12
	v_add_u32_e32 v70, s97, v251
	v_mov_b32_e32 v71, 0
	v_lshl_add_u64 v[70:71], v[152:153], 0, v[70:71]
	global_load_dwordx4 v[96:99], v[70:71], off
	v_lshrrev_b32_e32 v67, 3, v66
	v_add_u32_e32 v67, s96, v67
	v_and_b32_e32 v68, 7, v66
	v_lshlrev_b32_e32 v68, 4, v68
	s_and_b32 s97, s70, 3
	s_lshl_b32 s97, s97, 7
	v_add_u32_e32 v68, s97, v68
	v_lshl_add_u32 v253, v67, 9, v68
	v_add_u32_e32 v253, s9, v253
	v_sub_u32_e32 v69, 63, v67
	v_cndmask_b32_e64 v67, v69, v67, s[2:3]
	v_lshl_add_u32 v252, v67, 11, v68
	v_mbcnt_lo_u32_b32 v64, -1, 0
	v_mbcnt_hi_u32_b32 v64, -1, v64
	s_cmp_gt_u32 s70, 0
	s_cselect_b32 s97, 1.0, 0
	v_mov_b32_e32 v238, s97
	s_cmp_gt_u32 s70, 1
	s_cselect_b32 s97, 1.0, 0
	v_mov_b32_e32 v239, s97
	s_cmp_gt_u32 s70, 2
	s_cselect_b32 s97, 1.0, 0
	v_mov_b32_e32 v240, s97
	s_cmp_gt_u32 s70, 3
	s_cselect_b32 s97, 1.0, 0
	v_mov_b32_e32 v241, s97
	s_cmp_gt_u32 s70, 4
	s_cselect_b32 s97, 1.0, 0
	v_mov_b32_e32 v242, s97
	s_cmp_gt_u32 s70, 5
	s_cselect_b32 s97, 1.0, 0
	v_mov_b32_e32 v243, s97
	s_cmp_gt_u32 s70, 6
	s_cselect_b32 s97, 1.0, 0
	v_mov_b32_e32 v244, s97
	s_mul_i32 s99, s70, 0x880
	v_and_b32_e32 v66, 2, v64
	v_lshlrev_b32_e32 v66, 1, v66
	v_and_b32_e32 v67, 4, v64
	v_lshrrev_b32_e32 v67, 1, v67
	v_and_b32_e32 v70, 0xfffffff9, v64
	v_or3_b32 v66, v66, v67, v70
	v_lshl_add_u32 v254, v66, 2, s99
	s_lshr_b32 s98, s70, 1
	s_lshl_b32 s98, s98, 12
	s_and_b32 s99, s70, 1
	s_lshl_b32 s99, s99, 8
	s_add_i32 s98, s98, s99
	v_lshrrev_b32_e32 v66, 4, v64
	v_lshlrev_b32_e32 v66, 9, v66
	v_and_b32_e32 v70, 15, v64
	v_lshl_add_u32 v66, v70, 2, v66
	v_add_u32_e32 v255, s98, v66
	s_lshr_b32 s98, s70, 2
	s_lshl_b32 s98, s98, 12
	s_and_b32 s99, s70, 3
	s_lshl_b32 s99, s99, 7
	s_add_i32 s98, s98, s99
	s_add_i32 s98, s98, 0x20000
	v_lshrrev_b32_e32 v66, 5, v64
	v_lshlrev_b32_e32 v66, 9, v66
	v_and_b32_e32 v70, 31, v64
	v_lshl_add_u32 v66, v70, 2, v66
	v_add_u32_e32 v169, s98, v66
	v_mbcnt_lo_u32_b32 v64, -1, 0
	v_mbcnt_hi_u32_b32 v64, -1, v64
	v_lshrrev_b32_e32 v66, 5, v64
	v_lshlrev_b32_e32 v66, 11, v66
	v_and_b32_e32 v67, 31, v64
	v_lshlrev_b32_e32 v70, 1, v67
	v_add3_u32 v66, s49, v66, v70
	v_and_b32_e32 v67, 1, v67
	v_mul_u32_u24_e32 v67, 0x1fe, v67
	v_add_u32_e32 v246, v66, v67
	s_waitcnt vmcnt(0)
; __device__ __forceinline__ int crow(int r, int hi) { return (r & 3) + 8 * (r >> 2) + 4 * hi; }
; #define OPAQUE_TID(name) int name = MK_TID; asm volatile("" : "+v"(name))
; __device__ __forceinline__ void scan_unit(const int unit, const Args& a, unsigned char* lds, const int mk_wid) {
;     ...
;         { OPAQUE_TID(t_); const int lane = t_ & 63, r32 = lane & 31, hi = lane >> 5; const int tt = wid >> 2, ct = wid & 3;
;           const bf16x8 af = *(const bf16x8*)(lds + L_LR + (tt * 32 + r32) * 32 + hi * 16);
;           const f32x16 z = __builtin_amdgcn_mfma_f32_32x32x16_bf16(af, upf, f32x16{}, 0, 0, 0);
;           float* lw = las + (tt * 32 + 4 * hi) * 128 + ct * 32 + r32;
; #pragma unroll
;           for (int r = 0; r < 16; ++r) { const float zz = z[r] + biasc;
;               lw[crow(r, 0) * 128] = (fminf(zz, 0.f) - __builtin_amdgcn_logf(1.f + __builtin_amdgcn_exp2f(-1.4426950408889634f * fabsf(zz))) * 0.6931471805599453f) * (1.f / 16.f); } }
	v_mfma_f32_32x32x16_bf16 v[112:127], v[96:99], v[108:111], 0
	s_mov_b32 s96, 1.0
	s_mov_b32 s97, 0xbf317218
	s_mov_b32 s98, 0x3db8aa3b
	s_nop 11
	v_pk_add_f32 v[112:113], v[112:113], v[156:157] op_sel_hi:[1,0]
	v_pk_add_f32 v[114:115], v[114:115], v[156:157] op_sel_hi:[1,0]
	v_mul_f32_e64 v234, |v112|, s54
	v_mul_f32_e64 v235, |v113|, s54
	v_mul_f32_e64 v166, |v114|, s54
	v_mul_f32_e64 v167, |v115|, s54
	v_exp_f32_e32 v234, v234
	v_exp_f32_e32 v235, v235
	v_exp_f32_e32 v166, v166
	v_exp_f32_e32 v167, v167
	v_pk_add_f32 v[234:235], v[234:235], s[96:97] op_sel_hi:[1,0]
	v_pk_add_f32 v[166:167], v[166:167], s[96:97] op_sel_hi:[1,0]
	v_log_f32_e32 v234, v234
	v_log_f32_e32 v235, v235
	v_log_f32_e32 v166, v166
	v_log_f32_e32 v167, v167
	v_min_f32_e32 v112, 0, v112
	v_min_f32_e32 v113, 0, v113
	v_min_f32_e32 v114, 0, v114
	v_min_f32_e32 v115, 0, v115
	v_pk_fma_f32 v[112:113], v[234:235], s[96:97], v[112:113] op_sel:[0,1,0] op_sel_hi:[1,1,1]
	v_pk_fma_f32 v[114:115], v[166:167], s[96:97], v[114:115] op_sel:[0,1,0] op_sel_hi:[1,1,1]
	v_pk_mul_f32 v[112:113], v[112:113], s[98:99] op_sel_hi:[1,0]
	v_pk_mul_f32 v[114:115], v[114:115], s[98:99] op_sel_hi:[1,0]
	v_pk_add_f32 v[116:117], v[116:117], v[156:157] op_sel_hi:[1,0]
	v_pk_add_f32 v[118:119], v[118:119], v[156:157] op_sel_hi:[1,0]
	v_mul_f32_e64 v234, |v116|, s54
	v_mul_f32_e64 v235, |v117|, s54
	v_mul_f32_e64 v166, |v118|, s54
	v_mul_f32_e64 v167, |v119|, s54
	v_exp_f32_e32 v234, v234
	v_exp_f32_e32 v235, v235
	v_exp_f32_e32 v166, v166
	v_exp_f32_e32 v167, v167
	v_pk_add_f32 v[234:235], v[234:235], s[96:97] op_sel_hi:[1,0]
	v_pk_add_f32 v[166:167], v[166:167], s[96:97] op_sel_hi:[1,0]
	v_log_f32_e32 v234, v234
	v_log_f32_e32 v235, v235
	v_log_f32_e32 v166, v166
	v_log_f32_e32 v167, v167
	v_min_f32_e32 v116, 0, v116
	v_min_f32_e32 v117, 0, v117
	v_min_f32_e32 v118, 0, v118
	v_min_f32_e32 v119, 0, v119
	v_pk_fma_f32 v[116:117], v[234:235], s[96:97], v[116:117] op_sel:[0,1,0] op_sel_hi:[1,1,1]
	v_pk_fma_f32 v[118:119], v[166:167], s[96:97], v[118:119] op_sel:[0,1,0] op_sel_hi:[1,1,1]
	v_pk_mul_f32 v[116:117], v[116:117], s[98:99] op_sel_hi:[1,0]
	v_pk_mul_f32 v[118:119], v[118:119], s[98:99] op_sel_hi:[1,0]
	v_pk_add_f32 v[120:121], v[120:121], v[156:157] op_sel_hi:[1,0]
	v_pk_add_f32 v[122:123], v[122:123], v[156:157] op_sel_hi:[1,0]
	v_mul_f32_e64 v234, |v120|, s54
	v_mul_f32_e64 v235, |v121|, s54
	v_mul_f32_e64 v166, |v122|, s54
	v_mul_f32_e64 v167, |v123|, s54
	v_exp_f32_e32 v234, v234
	v_exp_f32_e32 v235, v235
	v_exp_f32_e32 v166, v166
	v_exp_f32_e32 v167, v167
	v_pk_add_f32 v[234:235], v[234:235], s[96:97] op_sel_hi:[1,0]
	v_pk_add_f32 v[166:167], v[166:167], s[96:97] op_sel_hi:[1,0]
	v_log_f32_e32 v234, v234
	v_log_f32_e32 v235, v235
	v_log_f32_e32 v166, v166
	v_log_f32_e32 v167, v167
	v_min_f32_e32 v120, 0, v120
	v_min_f32_e32 v121, 0, v121
	v_min_f32_e32 v122, 0, v122
	v_min_f32_e32 v123, 0, v123
	v_pk_fma_f32 v[120:121], v[234:235], s[96:97], v[120:121] op_sel:[0,1,0] op_sel_hi:[1,1,1]
	v_pk_fma_f32 v[122:123], v[166:167], s[96:97], v[122:123] op_sel:[0,1,0] op_sel_hi:[1,1,1]
	v_pk_mul_f32 v[120:121], v[120:121], s[98:99] op_sel_hi:[1,0]
	v_pk_mul_f32 v[122:123], v[122:123], s[98:99] op_sel_hi:[1,0]
	v_pk_add_f32 v[124:125], v[124:125], v[156:157] op_sel_hi:[1,0]
	v_pk_add_f32 v[126:127], v[126:127], v[156:157] op_sel_hi:[1,0]
	v_mul_f32_e64 v234, |v124|, s54
	v_mul_f32_e64 v235, |v125|, s54
	v_mul_f32_e64 v166, |v126|, s54
	v_mul_f32_e64 v167, |v127|, s54
	v_exp_f32_e32 v234, v234
	v_exp_f32_e32 v235, v235
	v_exp_f32_e32 v166, v166
	v_exp_f32_e32 v167, v167
	v_pk_add_f32 v[234:235], v[234:235], s[96:97] op_sel_hi:[1,0]
	v_pk_add_f32 v[166:167], v[166:167], s[96:97] op_sel_hi:[1,0]
	v_log_f32_e32 v234, v234
	v_log_f32_e32 v235, v235
	v_log_f32_e32 v166, v166
	v_log_f32_e32 v167, v167
	v_min_f32_e32 v124, 0, v124
	v_min_f32_e32 v125, 0, v125
	v_min_f32_e32 v126, 0, v126
	v_min_f32_e32 v127, 0, v127
	v_pk_fma_f32 v[124:125], v[234:235], s[96:97], v[124:125] op_sel:[0,1,0] op_sel_hi:[1,1,1]
	v_pk_fma_f32 v[126:127], v[166:167], s[96:97], v[126:127] op_sel:[0,1,0] op_sel_hi:[1,1,1]
	v_pk_mul_f32 v[124:125], v[124:125], s[98:99] op_sel_hi:[1,0]
	v_pk_mul_f32 v[126:127], v[126:127], s[98:99] op_sel_hi:[1,0]
	v_pk_add_f32 v[234:235], v[112:113], v[114:115]
	v_pk_add_f32 v[166:167], v[116:117], v[118:119]
	v_add_f32_e32 v234, v234, v235
	v_add_f32_e32 v166, v166, v167
	ds_write2st64_b32 v169, v234, v166 offset1:4
	v_pk_add_f32 v[234:235], v[120:121], v[122:123]
	v_pk_add_f32 v[166:167], v[124:125], v[126:127]
	v_add_f32_e32 v234, v234, v235
	v_add_f32_e32 v166, v166, v167
	ds_write2st64_b32 v169, v234, v166 offset0:8 offset1:12

; __device__ __forceinline__ int crow(int r, int hi) { return (r & 3) + 8 * (r >> 2) + 4 * hi; }
; #define OPAQUE_TID(name) int name = MK_TID; asm volatile("" : "+v"(name))
; __device__ __forceinline__ void scan_unit(const int unit, const Args& a, unsigned char* lds, const int mk_wid) {
;     ...
;         const int cc = GLA_CHUNK(step); const bool lat = cc >= 4;
;         GLA_FLUSH();
;         { OPAQUE_TID(t_);
; #pragma unroll
;           for (int p = 0; p < 2; ++p) { const int i_ = p * 32 + (t_ >> 4), c_ = (t_ & 15) * 8; *(bf16x8*)(qe + i_ * QP + c_) = qraw[p]; *(bf16x8*)(ke + i_ * QP + c_) = kraw[p]; }
; #pragma unroll
;           for (int p = 0; p < 4; ++p) { const int i_ = p * 16 + (t_ >> 5), c8 = t_ & 31; *(bf16x8*)(lds + L_V + (c8 >> 4) * 16384 + v_st(i_, (c8 & 15) * 8)) = vraw[p]; }
;           if (t_ < 128) *(bf16x8*)(lds + L_LR + (t_ >> 1) * 32 + (t_ & 1) * 16) = lraw; }
;         __syncthreads();
;         { OPAQUE_TID(t_); const int lane = t_ & 63, r32 = lane & 31, hi = lane >> 5; const int tt = wid >> 2, ct = wid & 3;
;           const bf16x8 af = *(const bf16x8*)(lds + L_LR + (tt * 32 + r32) * 32 + hi * 16);
;           const f32x16 z = __builtin_amdgcn_mfma_f32_32x32x16_bf16(af, upf, f32x16{}, 0, 0, 0);
;           float* lw = las + (tt * 32 + 4 * hi) * 128 + ct * 32 + r32;
; #pragma unroll
;           for (int r = 0; r < 16; ++r) { const float zz = z[r] + biasc;
;               lw[crow(r, 0) * 128] = (fminf(zz, 0.f) - __builtin_amdgcn_logf(1.f + __builtin_amdgcn_exp2f(-1.4426950408889634f * fabsf(zz))) * 0.6931471805599453f) * (1.f / 16.f); } }
;         __syncthreads();
;         { OPAQUE_TID(t_); const int c = t_ & 127, g = t_ >> 7;
;           float bl[16]; float run = 0.f;
;           { const float* lp = las + (g * 16) * 128 + c;
; #pragma unroll
;             for (int ii = 0; ii < 16; ++ii) { run += lp[ii * 128]; bl[ii] = run; } }
;           gs[g * 128 + c] = run;
;           __syncthreads();
;           const float g0 = gs[c], g1 = gs[128 + c], g2 = gs[256 + c], g3 = gs[384 + c];
;           const float off = (g > 0 ? g0 : 0.f) + (g > 1 ? g1 : 0.f) + (g > 2 ? g2 : 0.f);
;           const float btot = (g0 + g1) + (g2 + g3);
;           const float dlc = __builtin_amdgcn_exp2f(btot * 1.4426950408889634f);
;           if (g == 0) dl[c] = dlc;
.Lscan_cc_done:
	s_lshl_b32 s96, s96, 17
	s_lshl_b32 s97, s70, 12
	s_add_i32 s97, s97, 0xc800
	s_waitcnt vmcnt(0)
	s_cmp_eq_u32 s50, 3
	s_cbranch_scc1 .Lscan_nolr1
	s_add_i32 s98, s5, 1
	s_bitcmp1_b32 s8, 0
	s_cbranch_scc0 .Lscan_lr1_fwd
	s_cmp_gt_u32 s98, 3
	s_cselect_b32 s99, 39, 3
	s_sub_i32 s98, s99, s98
.Lscan_lr1_fwd:
	s_lshl_b32 s98, s98, 12
	v_add_u32_e32 v70, s98, v251
	v_mov_b32_e32 v71, 0
	v_lshl_add_u64 v[70:71], v[152:153], 0, v[70:71]
	global_load_dwordx4 v[96:99], v[70:71], off
.Lscan_nolr1:
	s_cmp_lt_i32 s34, 0
	s_cbranch_scc1 .Lscan_noflrd
	ds_read_b128 v[64:67], v253
	ds_read_b128 v[68:71], v253 offset:4096
	ds_read_b128 v[72:75], v253 offset:8192
	ds_read_b128 v[76:79], v253 offset:12288
	s_ashr_i32 s35, s34, 31
	s_lshl_b64 s[26:27], s[34:35], 6
	s_add_u32 s26, s26, s20
	s_addc_u32 s27, s27, s21
	s_add_u32 s26, s26, 0xffffff00
	s_addc_u32 s27, s27, -1
	s_lshl_b64 s[26:27], s[26:27], 11
	s_add_u32 s26, s26, s18
	s_addc_u32 s27, s27, s19
	s_movk_i32 s98, 0x4000
	s_movk_i32 s99, 0xc000
	s_bitcmp1_b32 s8, 0
	s_cselect_b32 s98, s99, s98
	v_add_u32_e32 v165, s98, v252
	v_add_u32_e32 v166, s98, v165
	v_add_u32_e32 v167, s98, v166
.Lscan_noflrd:
	v_add_u32_e32 v82, s96, v247
	v_add_u32_e32 v83, s96, v248
	v_add_u32_e32 v84, s96, v249
	v_add_u32_e32 v85, s96, v250
	s_mov_b32 m0, s97
	s_nop 0
	global_load_lds_dwordx4 v82, s[16:17]
	s_add_i32 m0, s97, 0x400
	s_nop 0
	global_load_lds_dwordx4 v83, s[16:17]
	s_add_i32 m0, s97, 0x800
	s_nop 0
	global_load_lds_dwordx4 v84, s[16:17]
	s_add_i32 m0, s97, 0xc00
	s_nop 0
	global_load_lds_dwordx4 v85, s[16:17]
	v_mbcnt_lo_u32_b32 v86, -1, 0
	v_mbcnt_hi_u32_b32 v86, -1, v86
	v_and_b32_e32 v87, 31, v86
	v_bfe_u32 v88, v86, 5, 1
	v_lshlrev_b32_e32 v88, 11, v88
	v_lshlrev_b32_e32 v87, 2, v87
	v_add3_u32 v80, s45, v88, v87
	s_cmp_lt_i32 s34, 0
	s_cbranch_scc1 .Lscan_noflush
	s_waitcnt lgkmcnt(3)
	global_store_dwordx4 v252, v[64:67], s[26:27]
	s_waitcnt lgkmcnt(2)
	global_store_dwordx4 v165, v[68:71], s[26:27]
	s_waitcnt lgkmcnt(1)
	global_store_dwordx4 v166, v[72:75], s[26:27]
	s_waitcnt lgkmcnt(0)
	global_store_dwordx4 v167, v[76:79], s[26:27]
.Lscan_noflush:
	ds_write2st64_b32 v80, v112, v113 offset1:2
	ds_write2st64_b32 v80, v114, v115 offset0:4 offset1:6
	ds_write2st64_b32 v80, v116, v117 offset0:16 offset1:18
	ds_write2st64_b32 v80, v118, v119 offset0:20 offset1:22
	ds_write2st64_b32 v80, v120, v121 offset0:32 offset1:34
	ds_write2st64_b32 v80, v122, v123 offset0:36 offset1:38
	ds_write2st64_b32 v80, v124, v125 offset0:48 offset1:50
	ds_write2st64_b32 v80, v126, v127 offset0:52 offset1:54
	s_waitcnt lgkmcnt(0)
	s_barrier
	v_mbcnt_lo_u32_b32 v64, -1, 0
	v_mbcnt_hi_u32_b32 v64, -1, v64
	s_lshl_b32 s96, s70, 12
	s_add_i32 s96, s96, s9
	v_lshl_add_u32 v65, v64, 3, s96
	v_lshlrev_b32_e32 v67, 3, v64
	v_add_u32_e32 v67, 0x20000, v67
	ds_read2st64_b64 v[186:189], v67 offset1:1
	ds_read2st64_b64 v[190:193], v67 offset0:2 offset1:3
	ds_read2st64_b64 v[194:197], v67 offset0:4 offset1:5
	ds_read2st64_b64 v[198:201], v67 offset0:6 offset1:7
	ds_read2st64_b64 v[202:205], v67 offset0:8 offset1:9
	ds_read2st64_b64 v[206:209], v67 offset0:10 offset1:11
	ds_read2st64_b64 v[210:213], v67 offset0:12 offset1:13
	ds_read2st64_b64 v[214:217], v67 offset0:14 offset1:15
	ds_read2st64_b64 v[170:173], v65 offset1:1
	ds_read2st64_b64 v[174:177], v65 offset0:2 offset1:3
	ds_read2st64_b64 v[178:181], v65 offset0:4 offset1:5
	ds_read2st64_b64 v[182:185], v65 offset0:6 offset1:7
	s_waitcnt lgkmcnt(4)
	v_pk_add_f32 v[72:73], v[186:187], v[188:189]
	v_pk_add_f32 v[74:75], v[190:191], v[192:193]
	v_pk_add_f32 v[76:77], v[194:195], v[196:197]
	v_pk_add_f32 v[78:79], v[198:199], v[200:201]
	v_pk_add_f32 v[80:81], v[202:203], v[204:205]
	v_pk_add_f32 v[82:83], v[206:207], v[208:209]
	v_pk_add_f32 v[84:85], v[210:211], v[212:213]
	v_pk_add_f32 v[86:87], v[214:215], v[216:217]
	v_pk_mul_f32 v[88:89], v[238:239], v[72:73] op_sel:[0,0] op_sel_hi:[0,1]
	v_pk_fma_f32 v[88:89], v[238:239], v[74:75], v[88:89] op_sel:[1,0,0] op_sel_hi:[1,1,1]
	v_pk_fma_f32 v[88:89], v[240:241], v[76:77], v[88:89] op_sel:[0,0,0] op_sel_hi:[0,1,1]
	v_pk_fma_f32 v[88:89], v[240:241], v[78:79], v[88:89] op_sel:[1,0,0] op_sel_hi:[1,1,1]
	v_pk_fma_f32 v[88:89], v[242:243], v[80:81], v[88:89] op_sel:[0,0,0] op_sel_hi:[0,1,1]
	v_pk_fma_f32 v[88:89], v[242:243], v[82:83], v[88:89] op_sel:[1,0,0] op_sel_hi:[1,1,1]
	v_pk_fma_f32 v[88:89], v[244:245], v[84:85], v[88:89] op_sel:[0,0,0] op_sel_hi:[0,1,1]
	v_pk_add_f32 v[90:91], v[72:73], v[74:75]
	v_pk_add_f32 v[90:91], v[90:91], v[76:77]
	v_pk_add_f32 v[90:91], v[90:91], v[78:79]
	v_pk_add_f32 v[90:91], v[90:91], v[80:81]
	v_pk_add_f32 v[90:91], v[90:91], v[82:83]
	v_pk_add_f32 v[90:91], v[90:91], v[84:85]
	v_pk_add_f32 v[90:91], v[90:91], v[86:87]
	v_mov_b64_e32 v[92:93], v[90:91]
	v_exp_f32_e32 v92, v92
	v_exp_f32_e32 v93, v93
	s_waitcnt lgkmcnt(0)
	v_pk_add_f32 v[170:171], v[170:171], v[88:89]
	v_pk_add_f32 v[172:173], v[172:173], v[170:171]
	v_pk_add_f32 v[174:175], v[174:175], v[172:173]
	v_pk_add_f32 v[176:177], v[176:177], v[174:175]
	v_pk_add_f32 v[178:179], v[178:179], v[176:177]
	v_pk_add_f32 v[180:181], v[180:181], v[178:179]
	v_pk_add_f32 v[182:183], v[182:183], v[180:181]
	v_pk_add_f32 v[184:185], v[184:185], v[182:183]
	v_exp_f32_e32 v170, v170
	v_exp_f32_e32 v171, v171
	v_exp_f32_e32 v172, v172
	v_exp_f32_e32 v173, v173
	v_exp_f32_e32 v174, v174
	v_exp_f32_e32 v175, v175
	v_exp_f32_e32 v176, v176
	v_exp_f32_e32 v177, v177
	v_exp_f32_e32 v178, v178
	v_exp_f32_e32 v179, v179
	v_exp_f32_e32 v180, v180
	v_exp_f32_e32 v181, v181
	v_exp_f32_e32 v182, v182
	v_exp_f32_e32 v183, v183
	v_exp_f32_e32 v184, v184
	v_exp_f32_e32 v185, v185
	v_rcp_f32_e32 v186, v170
	v_rcp_f32_e32 v187, v171
	v_rcp_f32_e32 v188, v172
	v_rcp_f32_e32 v189, v173
	v_rcp_f32_e32 v190, v174
	v_rcp_f32_e32 v191, v175
	v_rcp_f32_e32 v192, v176
	v_rcp_f32_e32 v193, v177
	v_rcp_f32_e32 v194, v178
	v_rcp_f32_e32 v195, v179
	v_rcp_f32_e32 v196, v180
	v_rcp_f32_e32 v197, v181
	v_rcp_f32_e32 v198, v182
	v_rcp_f32_e32 v199, v183
	v_rcp_f32_e32 v200, v184
	v_rcp_f32_e32 v201, v185
	s_mov_b32 s96, 0x3db504f3
	s_mov_b32 s97, s96
	v_pk_mul_f32 v[170:171], v[170:171], s[96:97]
	v_pk_mul_f32 v[172:173], v[172:173], s[96:97]
	v_pk_mul_f32 v[174:175], v[174:175], s[96:97]
	v_pk_mul_f32 v[176:177], v[176:177], s[96:97]
	v_pk_mul_f32 v[178:179], v[178:179], s[96:97]
	v_pk_mul_f32 v[180:181], v[180:181], s[96:97]
	v_pk_mul_f32 v[182:183], v[182:183], s[96:97]
	v_pk_mul_f32 v[184:185], v[184:185], s[96:97]
	s_cmp_lg_u32 s70, 0
	s_cbranch_scc1 .Lscan_c2_nodl
	v_lshlrev_b32_e32 v70, 3, v64
	v_add_u32_e32 v70, 0x1fc00, v70
	ds_write_b64 v70, v[92:93]

; __device__ __forceinline__ unsigned pk2(float lo, float hi) { f32x2_t v = {lo, hi}; bf16x2_t b = __builtin_convertvector(v, bf16x2_t); return __builtin_bit_cast(unsigned, b); }
; #define OPAQUE_TID(name) int name = MK_TID; asm volatile("" : "+v"(name))
; __device__ __forceinline__ void scan_unit(const int unit, const Args& a, unsigned char* lds, const int mk_wid) {
;     ...
;         if (step + 1 < 36) GLA_LOAD(step + 1);
;         __syncthreads();
;         if (lat) {
;             if (wid < 4) { OPAQUE_TID(t_); const int r32 = t_ & 31, hi = (t_ >> 5) & 1;
;                 const int jt = wid >> 1, it = wid & 1; f32x16 ct = f32x16{};
;                 const u16* kp = ke + (jt * 32 + r32) * QP + hi * 8; const u16* qp = qe + (it * 32 + r32) * QP + hi * 8;
; #pragma unroll
;                 for (int kb = 0; kb < 8; ++kb) ct = __builtin_amdgcn_mfma_f32_32x32x16_bf16(*(const bf16x8*)(kp + kb * 16), *(const bf16x8*)(qp + kb * 16), ct, 0, 0, 0);
;                 const int i = it * 32 + r32;
; #pragma unroll
;                 for (int rg = 0; rg < 4; ++rg) { const int j0 = jt * 32 + 8 * rg + 4 * hi;
;                     const float x0 = (j0 + 0 <= i) ? ct[4 * rg + 0] : 0.f, x1 = (j0 + 1 <= i) ? ct[4 * rg + 1] : 0.f, x2 = (j0 + 2 <= i) ? ct[4 * rg + 2] : 0.f, x3 = (j0 + 3 <= i) ? ct[4 * rg + 3] : 0.f;
;                     v2u w; w.x = pk2(x0, x1); w.y = pk2(x2, x3); *(v2u*)(am + i * AP + j0) = w; } }
.Lscan_pf_v:
.Lscan_pf_nolr:
.LBB0_435:
	s_cmp_gt_u32 s5, 3
	s_cselect_b32 s4, 39, 3
	s_add_i32 s4, s4, s50
	s_sub_i32 s4, s4, 38
	s_and_b64 s[26:27], s[2:3], exec
	s_cselect_b32 s42, s5, s4
	s_cmp_gt_i32 s42, 3
	s_cselect_b64 s[26:27], -1, 0
	s_cmp_lt_i32 s42, 4
	s_cselect_b64 s[34:35], -1, 0
	s_and_b64 vcc, exec, s[34:35]
	s_waitcnt lgkmcnt(0)
	s_barrier
	s_cbranch_vccnz .LBB0_439
	s_andn2_b64 vcc, exec, s[24:25]
	s_cbranch_vccnz .LBB0_438
	v_mbcnt_lo_u32_b32 v64, -1, 0
	v_mbcnt_hi_u32_b32 v64, -1, v64
	s_nop 0
	v_add_u32_e32 v64, s72, v64
	s_nop 0
	v_and_b32_e32 v68, 31, v64
	v_bfe_u32 v154, v64, 5, 1
	v_or_b32_e32 v64, s46, v68
	v_mul_lo_u32 v64, v64, s51
	v_lshlrev_b32_e32 v69, 4, v154
	v_add3_u32 v157, 0, v64, v69
	v_or_b32_e32 v158, s47, v68
	v_mul_u32_u24_e32 v68, 0x110, v158
	v_add3_u32 v159, 0, v68, v69
	ds_read_b128 v[170:173], v157 offset:17408
	ds_read_b128 v[174:177], v159
	ds_read_b128 v[178:181], v157 offset:17440
	ds_read_b128 v[182:185], v159 offset:32
	ds_read_b128 v[186:189], v157 offset:17472
	ds_read_b128 v[190:193], v159 offset:64
	ds_read_b128 v[194:197], v157 offset:17504
	ds_read_b128 v[198:201], v159 offset:96
	ds_read_b128 v[202:205], v157 offset:17536
	ds_read_b128 v[206:209], v159 offset:128
	ds_read_b128 v[210:213], v157 offset:17568
	ds_read_b128 v[214:217], v159 offset:160
	ds_read_b128 v[218:221], v157 offset:17600
	ds_read_b128 v[222:225], v159 offset:192
	ds_read_b128 v[226:229], v157 offset:17632
	v_lshl_or_b32 v154, v154, 2, s46
	v_cmp_le_u32_e32 vcc, v154, v158
	v_or_b32_e32 v161, 2, v154
	v_or_b32_e32 v162, 3, v154
	v_or_b32_e32 v164, 8, v154
	v_mul_u32_u24_e32 v160, 0x90, v158
	v_lshlrev_b32_e32 v163, 1, v154
	s_waitcnt lgkmcnt(13)
	v_mfma_f32_32x32x16_bf16 v[64:79], v[170:173], v[174:177], 0
	ds_read_b128 v[230:233], v159 offset:224
	v_or_b32_e32 v80, 10, v154
	v_or_b32_e32 v81, 11, v154
	v_or_b32_e32 v82, 16, v154
	v_or_b32_e32 v83, 18, v154
	v_or_b32_e32 v84, 19, v154
	v_or_b32_e32 v85, 24, v154
	v_add3_u32 v86, s57, v160, v163
	s_waitcnt lgkmcnt(12)
	v_mfma_f32_32x32x16_bf16 v[64:79], v[178:181], v[182:185], v[64:79]
	s_waitcnt lgkmcnt(10)
	v_mfma_f32_32x32x16_bf16 v[64:79], v[186:189], v[190:193], v[64:79]
	s_waitcnt lgkmcnt(8)
	v_mfma_f32_32x32x16_bf16 v[64:79], v[194:197], v[198:201], v[64:79]
	s_waitcnt lgkmcnt(6)
	v_mfma_f32_32x32x16_bf16 v[64:79], v[202:205], v[206:209], v[64:79]
	s_waitcnt lgkmcnt(4)
	v_mfma_f32_32x32x16_bf16 v[64:79], v[210:213], v[214:217], v[64:79]
	s_waitcnt lgkmcnt(2)
	v_mfma_f32_32x32x16_bf16 v[64:79], v[218:221], v[222:225], v[64:79]
	s_waitcnt lgkmcnt(0)
	v_mfma_f32_32x32x16_bf16 v[64:79], v[226:229], v[230:233], v[64:79]
	s_nop 11
	v_cndmask_b32_e32 v64, 0, v64, vcc
	v_cmp_lt_u32_e32 vcc, v154, v158
	s_nop 1
	v_cndmask_b32_e32 v65, 0, v65, vcc
	v_cmp_le_u32_e32 vcc, v161, v158
	v_cvt_pk_bf16_f32 v64, v64, v65
	s_nop 0
	v_cndmask_b32_e32 v66, 0, v66, vcc
	v_cmp_le_u32_e32 vcc, v162, v158
	s_nop 1
	v_cndmask_b32_e32 v67, 0, v67, vcc
	v_cmp_le_u32_e32 vcc, v164, v158
	v_cvt_pk_bf16_f32 v65, v66, v67
	s_nop 0
	v_cndmask_b32_e32 v68, 0, v68, vcc
	v_cmp_lt_u32_e32 vcc, v164, v158
	s_nop 1
	v_cndmask_b32_e32 v69, 0, v69, vcc
	v_cmp_le_u32_e32 vcc, v80, v158
	v_cvt_pk_bf16_f32 v66, v68, v69
	s_nop 0
	v_cndmask_b32_e32 v70, 0, v70, vcc
	v_cmp_le_u32_e32 vcc, v81, v158
	s_nop 1
	v_cndmask_b32_e32 v71, 0, v71, vcc
	v_cmp_le_u32_e32 vcc, v82, v158
	v_cvt_pk_bf16_f32 v67, v70, v71
	ds_write2_b64 v86, v[64:65], v[66:67] offset1:2
	v_cndmask_b32_e32 v72, 0, v72, vcc
	v_cmp_lt_u32_e32 vcc, v82, v158
	v_or_b32_e32 v65, 26, v154
	v_or_b32_e32 v66, 27, v154
	v_cndmask_b32_e32 v73, 0, v73, vcc
	v_cmp_le_u32_e32 vcc, v83, v158
	v_cvt_pk_bf16_f32 v68, v72, v73
	s_nop 0
	v_cndmask_b32_e32 v74, 0, v74, vcc
	v_cmp_le_u32_e32 vcc, v84, v158
	s_nop 1
	v_cndmask_b32_e32 v75, 0, v75, vcc
	v_cmp_le_u32_e32 vcc, v85, v158
	v_cvt_pk_bf16_f32 v69, v74, v75
	s_nop 0
	v_cndmask_b32_e32 v76, 0, v76, vcc
	v_cmp_lt_u32_e32 vcc, v85, v158
	s_nop 1
	v_cndmask_b32_e32 v64, 0, v77, vcc
	v_cmp_le_u32_e32 vcc, v65, v158
	v_cvt_pk_bf16_f32 v64, v76, v64
	s_nop 0
	v_cndmask_b32_e32 v65, 0, v78, vcc
	v_cmp_le_u32_e32 vcc, v66, v158
	s_nop 1
	v_cndmask_b32_e32 v66, 0, v79, vcc
	v_cvt_pk_bf16_f32 v65, v65, v66
	ds_write2_b64 v86, v[68:69], v[64:65] offset0:4 offset1:6

; __device__ __forceinline__ int crow(int r, int hi) { return (r & 3) + 8 * (r >> 2) + 4 * hi; }
; __device__ __forceinline__ unsigned pk2(float lo, float hi) { f32x2_t v = {lo, hi}; bf16x2_t b = __builtin_convertvector(v, bf16x2_t); return __builtin_bit_cast(unsigned, b); }
; #define OPAQUE_TID(name) int name = MK_TID; asm volatile("" : "+v"(name))
; __device__ __forceinline__ void scan_unit(const int unit, const Args& a, unsigned char* lds, const int mk_wid) {
;     ...
;         { OPAQUE_TID(t_); const int lane = t_ & 63, r32 = lane & 31, hi = lane >> 5; const int tt = wid >> 2, ct = wid & 3;
;           const bf16x8 af = *(const bf16x8*)(lds + L_LR + (tt * 32 + r32) * 32 + hi * 16);
;           const f32x16 z = __builtin_amdgcn_mfma_f32_32x32x16_bf16(af, upf, f32x16{}, 0, 0, 0);
;           float* lw = las + (tt * 32 + 4 * hi) * 128 + ct * 32 + r32;
; #pragma unroll
;           for (int r = 0; r < 16; ++r) { const float zz = z[r] + biasc;
;               lw[crow(r, 0) * 128] = (fminf(zz, 0.f) - __builtin_amdgcn_logf(1.f + __builtin_amdgcn_exp2f(-1.4426950408889634f * fabsf(zz))) * 0.6931471805599453f) * (1.f / 16.f); } }
;     ...
;           if (lat) {
;               f32x16 o0 = f32x16{}, o1 = f32x16{};
; #pragma unroll
;               for (int ct = 0; ct < 4; ++ct)
; #pragma unroll
;                 for (int kb = 0; kb < 2; ++kb) { const int cb = ct * 32 + kb * 16;
;                     v4u sw; sw.x = pk2(S[ct][8 * kb + 0], S[ct][8 * kb + 1]); sw.y = pk2(S[ct][8 * kb + 2], S[ct][8 * kb + 3]); sw.z = pk2(S[ct][8 * kb + 4], S[ct][8 * kb + 5]); sw.w = pk2(S[ct][8 * kb + 6], S[ct][8 * kb + 7]);
;                     const bf16x8 sb = __builtin_bit_cast(bf16x8, sw);
;                     { const u16* p0 = qe + r32 * QP + cb + 4 * hi; const v2u lo = *(const v2u*)p0, hh = *(const v2u*)(p0 + 8); v4u aw = {lo.x, lo.y, hh.x, hh.y};
;                       o0 = __builtin_amdgcn_mfma_f32_32x32x16_bf16(__builtin_bit_cast(bf16x8, aw), sb, o0, 0, 0, 0); }
;                     { const u16* p1 = qe + (32 + r32) * QP + cb + 4 * hi; const v2u lo = *(const v2u*)p1, hh = *(const v2u*)(p1 + 8); v4u aw = {lo.x, lo.y, hh.x, hh.y};
;                       o1 = __builtin_amdgcn_mfma_f32_32x32x16_bf16(__builtin_bit_cast(bf16x8, aw), sb, o1, 0, 0, 0); } }
.LBB0_442:
	v_and_b32_e32 v168, 31, v64
	v_mul_u32_u24_e32 v64, 0x110, v168
	v_lshlrev_b32_e32 v65, 4, v157
	v_add3_u32 v144, 0, v64, v65
	ds_read_b128 v[170:173], v144
	ds_read_b128 v[174:177], v144 offset:32
	ds_read_b128 v[178:181], v144 offset:8704
	ds_read_b128 v[182:185], v144 offset:8736
	ds_read_b128 v[186:189], v144 offset:64
	ds_read_b128 v[190:193], v144 offset:8768
	ds_read_b128 v[194:197], v144 offset:96
	ds_read_b128 v[198:201], v144 offset:8800
	ds_read_b128 v[202:205], v144 offset:128
	ds_read_b128 v[206:209], v144 offset:8832
	ds_read_b128 v[210:213], v144 offset:160
	ds_read_b128 v[214:217], v144 offset:8864
	ds_read_b128 v[218:221], v144 offset:192
	ds_read_b128 v[222:225], v144 offset:8896
	ds_read_b128 v[226:229], v144 offset:224
	v_cvt_pk_bf16_f32 v80, v0, v1
	v_cvt_pk_bf16_f32 v81, v2, v3
	v_cvt_pk_bf16_f32 v82, v4, v5
	v_cvt_pk_bf16_f32 v83, v6, v7
	v_mfma_f32_32x32x16_bf16 v[112:127], v[96:99], v[108:111], 0
	s_mov_b32 s96, 1.0
	s_mov_b32 s97, 0xbf317218
	s_mov_b32 s98, 0x3db8aa3b
	s_waitcnt lgkmcnt(14)
	s_nop 0
	v_mfma_f32_32x32x16_bf16 v[64:79], v[170:173], v[80:83], 0
	ds_read_b128 v[230:233], v144 offset:8928
	v_cvt_pk_bf16_f32 v140, v8, v9
	v_cvt_pk_bf16_f32 v141, v10, v11
	v_cvt_pk_bf16_f32 v142, v12, v13
	v_cvt_pk_bf16_f32 v143, v14, v15
	v_cvt_pk_bf16_f32 v160, v56, v57
	v_cvt_pk_bf16_f32 v161, v58, v59
	v_cvt_pk_bf16_f32 v162, v60, v61
	v_cvt_pk_bf16_f32 v163, v62, v63
	s_waitcnt lgkmcnt(14)
	s_nop 0
	v_mfma_f32_32x32x16_bf16 v[64:79], v[174:177], v[140:143], v[64:79]
	s_waitcnt lgkmcnt(13)
	v_mfma_f32_32x32x16_bf16 v[80:95], v[178:181], v[80:83], 0
	v_pk_add_f32 v[112:113], v[112:113], v[156:157] op_sel_hi:[1,0]
	v_pk_add_f32 v[114:115], v[114:115], v[156:157] op_sel_hi:[1,0]
	v_mul_f32_e64 v234, |v112|, s54
	v_mul_f32_e64 v235, |v113|, s54
	v_mul_f32_e64 v166, |v114|, s54
	v_mul_f32_e64 v167, |v115|, s54
	s_waitcnt lgkmcnt(12)
	v_mfma_f32_32x32x16_bf16 v[80:95], v[182:185], v[140:143], v[80:95]
	v_exp_f32_e32 v234, v234
	v_exp_f32_e32 v235, v235
	v_exp_f32_e32 v166, v166
	v_exp_f32_e32 v167, v167
	v_pk_add_f32 v[234:235], v[234:235], s[96:97] op_sel_hi:[1,0]
	v_pk_add_f32 v[166:167], v[166:167], s[96:97] op_sel_hi:[1,0]
	v_cvt_pk_bf16_f32 v140, v16, v17
	v_cvt_pk_bf16_f32 v141, v18, v19
	v_cvt_pk_bf16_f32 v142, v20, v21
	v_cvt_pk_bf16_f32 v143, v22, v23
	s_waitcnt lgkmcnt(11)
	s_nop 0
	v_mfma_f32_32x32x16_bf16 v[64:79], v[186:189], v[140:143], v[64:79]
	v_log_f32_e32 v234, v234
	v_log_f32_e32 v235, v235
	v_log_f32_e32 v166, v166
	v_log_f32_e32 v167, v167
	v_min_f32_e32 v112, 0, v112
	v_min_f32_e32 v113, 0, v113
	s_waitcnt lgkmcnt(10)
	v_mfma_f32_32x32x16_bf16 v[80:95], v[190:193], v[140:143], v[80:95]
	v_min_f32_e32 v114, 0, v114
	v_min_f32_e32 v115, 0, v115
	v_pk_fma_f32 v[112:113], v[234:235], s[96:97], v[112:113] op_sel:[0,1,0] op_sel_hi:[1,1,1]
	v_pk_fma_f32 v[114:115], v[166:167], s[96:97], v[114:115] op_sel:[0,1,0] op_sel_hi:[1,1,1]
	v_pk_mul_f32 v[112:113], v[112:113], s[98:99] op_sel_hi:[1,0]
	v_pk_mul_f32 v[114:115], v[114:115], s[98:99] op_sel_hi:[1,0]
	v_cvt_pk_bf16_f32 v140, v24, v25
	v_cvt_pk_bf16_f32 v141, v26, v27
	v_cvt_pk_bf16_f32 v142, v28, v29
	v_cvt_pk_bf16_f32 v143, v30, v31
	s_waitcnt lgkmcnt(9)
	s_nop 0
	v_mfma_f32_32x32x16_bf16 v[64:79], v[194:197], v[140:143], v[64:79]
	v_pk_add_f32 v[116:117], v[116:117], v[156:157] op_sel_hi:[1,0]
	v_pk_add_f32 v[118:119], v[118:119], v[156:157] op_sel_hi:[1,0]
	v_mul_f32_e64 v234, |v116|, s54
	v_mul_f32_e64 v235, |v117|, s54
	v_mul_f32_e64 v166, |v118|, s54
	v_mul_f32_e64 v167, |v119|, s54
	s_waitcnt lgkmcnt(8)
	v_mfma_f32_32x32x16_bf16 v[80:95], v[198:201], v[140:143], v[80:95]
	v_exp_f32_e32 v234, v234
	v_exp_f32_e32 v235, v235
	v_exp_f32_e32 v166, v166
	v_exp_f32_e32 v167, v167
	v_pk_add_f32 v[234:235], v[234:235], s[96:97] op_sel_hi:[1,0]
	v_pk_add_f32 v[166:167], v[166:167], s[96:97] op_sel_hi:[1,0]
	v_cvt_pk_bf16_f32 v140, v32, v33
	v_cvt_pk_bf16_f32 v141, v34, v35
	v_cvt_pk_bf16_f32 v142, v36, v37
	v_cvt_pk_bf16_f32 v143, v38, v39
	s_waitcnt lgkmcnt(7)
	s_nop 0
	v_mfma_f32_32x32x16_bf16 v[64:79], v[202:205], v[140:143], v[64:79]
	v_log_f32_e32 v234, v234
	v_log_f32_e32 v235, v235
	v_log_f32_e32 v166, v166
	v_log_f32_e32 v167, v167
	v_min_f32_e32 v116, 0, v116
	v_min_f32_e32 v117, 0, v117
	s_waitcnt lgkmcnt(6)
	v_mfma_f32_32x32x16_bf16 v[80:95], v[206:209], v[140:143], v[80:95]
	v_min_f32_e32 v118, 0, v118
	v_min_f32_e32 v119, 0, v119
	v_pk_fma_f32 v[116:117], v[234:235], s[96:97], v[116:117] op_sel:[0,1,0] op_sel_hi:[1,1,1]
	v_pk_fma_f32 v[118:119], v[166:167], s[96:97], v[118:119] op_sel:[0,1,0] op_sel_hi:[1,1,1]
	v_pk_mul_f32 v[116:117], v[116:117], s[98:99] op_sel_hi:[1,0]
	v_pk_mul_f32 v[118:119], v[118:119], s[98:99] op_sel_hi:[1,0]
	v_cvt_pk_bf16_f32 v140, v40, v41
	v_cvt_pk_bf16_f32 v141, v42, v43
	v_cvt_pk_bf16_f32 v142, v44, v45
	v_cvt_pk_bf16_f32 v143, v46, v47
	s_waitcnt lgkmcnt(5)
	s_nop 0
	v_mfma_f32_32x32x16_bf16 v[64:79], v[210:213], v[140:143], v[64:79]
	v_pk_add_f32 v[120:121], v[120:121], v[156:157] op_sel_hi:[1,0]
	v_pk_add_f32 v[122:123], v[122:123], v[156:157] op_sel_hi:[1,0]
	v_mul_f32_e64 v234, |v120|, s54
	v_mul_f32_e64 v235, |v121|, s54
	v_mul_f32_e64 v166, |v122|, s54
	v_mul_f32_e64 v167, |v123|, s54
	s_waitcnt lgkmcnt(4)
	v_mfma_f32_32x32x16_bf16 v[80:95], v[214:217], v[140:143], v[80:95]
	v_exp_f32_e32 v234, v234
	v_exp_f32_e32 v235, v235
	v_exp_f32_e32 v166, v166
	v_exp_f32_e32 v167, v167
	v_pk_add_f32 v[234:235], v[234:235], s[96:97] op_sel_hi:[1,0]
	v_pk_add_f32 v[166:167], v[166:167], s[96:97] op_sel_hi:[1,0]
	v_cvt_pk_bf16_f32 v140, v48, v49
	v_cvt_pk_bf16_f32 v141, v50, v51
	v_cvt_pk_bf16_f32 v142, v52, v53
	v_cvt_pk_bf16_f32 v143, v54, v55
	s_waitcnt lgkmcnt(3)
	s_nop 0
	v_mfma_f32_32x32x16_bf16 v[64:79], v[218:221], v[140:143], v[64:79]
	v_log_f32_e32 v234, v234
	v_log_f32_e32 v235, v235
	v_log_f32_e32 v166, v166
	v_log_f32_e32 v167, v167
	v_min_f32_e32 v120, 0, v120
	v_min_f32_e32 v121, 0, v121
	s_waitcnt lgkmcnt(2)
	v_mfma_f32_32x32x16_bf16 v[80:95], v[222:225], v[140:143], v[80:95]
	v_min_f32_e32 v122, 0, v122
	v_min_f32_e32 v123, 0, v123
	v_pk_fma_f32 v[120:121], v[234:235], s[96:97], v[120:121] op_sel:[0,1,0] op_sel_hi:[1,1,1]
	v_pk_fma_f32 v[122:123], v[166:167], s[96:97], v[122:123] op_sel:[0,1,0] op_sel_hi:[1,1,1]
	v_pk_mul_f32 v[120:121], v[120:121], s[98:99] op_sel_hi:[1,0]
	v_pk_mul_f32 v[122:123], v[122:123], s[98:99] op_sel_hi:[1,0]
	v_mul_u32_u24_e32 v236, 0x90, v168
	v_lshlrev_b32_e32 v237, 4, v157
	v_add3_u32 v236, s57, v236, v237
	s_waitcnt lgkmcnt(0)
	s_barrier
; __device__ __forceinline__ int crow(int r, int hi) { return (r & 3) + 8 * (r >> 2) + 4 * hi; }
; #define GLA_SBAR() __builtin_amdgcn_sched_barrier(0)
; #define GLA_LOADV() do { vl0 = tr_read<v_rd_off(0, 0, 0)>(vb); vh0 = tr_read<v_rd_off(0, 0, 1)>(vb); vl1 = tr_read<v_rd_off(0, 1, 0)>(vb); vh1 = tr_read<v_rd_off(0, 1, 1)>(vb); \
;               vl2 = tr_read<v_rd_off(0, 2, 0)>(vb); vh2 = tr_read<v_rd_off(0, 2, 1)>(vb); vl3 = tr_read<v_rd_off(0, 3, 0)>(vb); vh3 = tr_read<v_rd_off(0, 3, 1)>(vb); } while (0)
; __device__ __forceinline__ void scan_unit(const int unit, const Args& a, unsigned char* lds, const int mk_wid) {
;     ...
;           for (int r = 0; r < 16; ++r) { const float zz = z[r] + biasc;
;               lw[crow(r, 0) * 128] = (fminf(zz, 0.f) - __builtin_amdgcn_logf(1.f + __builtin_amdgcn_exp2f(-1.4426950408889634f * fabsf(zz))) * 0.6931471805599453f) * (1.f / 16.f); } }
;     ...
;               GLA_LOADV();
;               asm volatile("s_waitcnt lgkmcnt(0)" ::: "memory"); GLA_SBAR();
;               { const u16* a0 = am + r32 * AP + hi * 8; const u16* a1 = am + (32 + r32) * AP + hi * 8;
;                 o0 = __builtin_amdgcn_mfma_f32_32x32x16_bf16(*(const bf16x8*)(a0), GLA_PK(vl0, vh0), o0, 0, 0, 0);
;                 o0 = __builtin_amdgcn_mfma_f32_32x32x16_bf16(*(const bf16x8*)(a0 + 16), GLA_PK(vl1, vh1), o0, 0, 0, 0);
;                 o1 = __builtin_amdgcn_mfma_f32_32x32x16_bf16(*(const bf16x8*)(a1), GLA_PK(vl0, vh0), o1, 0, 0, 0);
;                 o1 = __builtin_amdgcn_mfma_f32_32x32x16_bf16(*(const bf16x8*)(a1 + 16), GLA_PK(vl1, vh1), o1, 0, 0, 0);
;                 o1 = __builtin_amdgcn_mfma_f32_32x32x16_bf16(*(const bf16x8*)(a1 + 32), GLA_PK(vl2, vh2), o1, 0, 0, 0);
;                 o1 = __builtin_amdgcn_mfma_f32_32x32x16_bf16(*(const bf16x8*)(a1 + 48), GLA_PK(vl3, vh3), o1, 0, 0, 0); }
	ds_read_b128 v[170:173], v236
	ds_read_b128 v[174:177], v236 offset:32
	ds_read_b128 v[178:181], v236 offset:4608
	ds_read_b128 v[182:185], v236 offset:4640
	ds_read_b128 v[186:189], v236 offset:4672
	ds_read_b128 v[190:193], v236 offset:4704
	ds_read_b64_tr_b16 v[136:137], v158 offset:0
	s_waitcnt lgkmcnt(8)
	v_mfma_f32_32x32x16_bf16 v[64:79], v[226:229], v[160:163], v[64:79]
	v_pk_add_f32 v[124:125], v[124:125], v[156:157] op_sel_hi:[1,0]
	v_pk_add_f32 v[126:127], v[126:127], v[156:157] op_sel_hi:[1,0]
	v_mul_f32_e64 v234, |v124|, s54
	v_mul_f32_e64 v235, |v125|, s54
	v_mul_f32_e64 v166, |v126|, s54
	v_mul_f32_e64 v167, |v127|, s54
	ds_read_b64_tr_b16 v[138:139], v158 offset:0x800
	ds_read_b64_tr_b16 v[140:141], v158 offset:0x1000
	ds_read_b64_tr_b16 v[142:143], v158 offset:0x1800
	ds_read_b64_tr_b16 v[144:145], v158 offset:0x2000
	ds_read_b64_tr_b16 v[146:147], v158 offset:0x2800
	ds_read_b64_tr_b16 v[148:149], v158 offset:0x3000
	ds_read_b64_tr_b16 v[150:151], v158 offset:0x3800
	s_waitcnt lgkmcnt(0)
	v_mfma_f32_32x32x16_bf16 v[80:95], v[230:233], v[160:163], v[80:95]
	v_exp_f32_e32 v234, v234
	v_exp_f32_e32 v235, v235
	v_exp_f32_e32 v166, v166
	v_exp_f32_e32 v167, v167
	v_pk_add_f32 v[234:235], v[234:235], s[96:97] op_sel_hi:[1,0]
	v_pk_add_f32 v[166:167], v[166:167], s[96:97] op_sel_hi:[1,0]
	s_mov_b32 s34, s42
	v_mfma_f32_32x32x16_bf16 v[64:79], v[170:173], v[136:139], v[64:79]
	v_log_f32_e32 v234, v234
	v_log_f32_e32 v235, v235
	v_log_f32_e32 v166, v166
	v_log_f32_e32 v167, v167
	v_min_f32_e32 v124, 0, v124
	v_min_f32_e32 v125, 0, v125
	v_mfma_f32_32x32x16_bf16 v[64:79], v[174:177], v[140:143], v[64:79]
	v_min_f32_e32 v126, 0, v126
	v_min_f32_e32 v127, 0, v127
	v_pk_fma_f32 v[124:125], v[234:235], s[96:97], v[124:125] op_sel:[0,1,0] op_sel_hi:[1,1,1]
	v_pk_fma_f32 v[126:127], v[166:167], s[96:97], v[126:127] op_sel:[0,1,0] op_sel_hi:[1,1,1]
	v_pk_mul_f32 v[124:125], v[124:125], s[98:99] op_sel_hi:[1,0]
	v_pk_mul_f32 v[126:127], v[126:127], s[98:99] op_sel_hi:[1,0]
	v_mfma_f32_32x32x16_bf16 v[80:95], v[178:181], v[136:139], v[80:95]
	v_pk_add_f32 v[234:235], v[112:113], v[114:115]
	v_pk_add_f32 v[166:167], v[116:117], v[118:119]
	v_add_f32_e32 v234, v234, v235
	v_add_f32_e32 v166, v166, v167
	ds_write2st64_b32 v169, v234, v166 offset1:4
	v_pk_add_f32 v[234:235], v[120:121], v[122:123]
	v_mfma_f32_32x32x16_bf16 v[80:95], v[182:185], v[140:143], v[80:95]
	v_pk_add_f32 v[166:167], v[124:125], v[126:127]
	v_add_f32_e32 v234, v234, v235
	v_add_f32_e32 v166, v166, v167
	ds_write2st64_b32 v169, v234, v166 offset0:8 offset1:12
	v_mfma_f32_32x32x16_bf16 v[80:95], v[186:189], v[144:147], v[80:95]
	v_mfma_f32_32x32x16_bf16 v[80:95], v[190:193], v[148:151], v[80:95]

; __device__ __forceinline__ int crow(int r, int hi) { return (r & 3) + 8 * (r >> 2) + 4 * hi; }
; #define OPAQUE_TID(name) int name = MK_TID; asm volatile("" : "+v"(name))
; __device__ __forceinline__ void scan_unit(const int unit, const Args& a, unsigned char* lds, const int mk_wid) {
;     ...
;         { OPAQUE_TID(t_); const int lane = t_ & 63, r32 = lane & 31, hi = lane >> 5; const int tt = wid >> 2, ct = wid & 3;
;           const bf16x8 af = *(const bf16x8*)(lds + L_LR + (tt * 32 + r32) * 32 + hi * 16);
;           const f32x16 z = __builtin_amdgcn_mfma_f32_32x32x16_bf16(af, upf, f32x16{}, 0, 0, 0);
;           float* lw = las + (tt * 32 + 4 * hi) * 128 + ct * 32 + r32;
; #pragma unroll
;           for (int r = 0; r < 16; ++r) { const float zz = z[r] + biasc;
;               lw[crow(r, 0) * 128] = (fminf(zz, 0.f) - __builtin_amdgcn_logf(1.f + __builtin_amdgcn_exp2f(-1.4426950408889634f * fabsf(zz))) * 0.6931471805599453f) * (1.f / 16.f); } }
.Lscan_b1ctx:
	v_mfma_f32_32x32x16_bf16 v[112:127], v[96:99], v[108:111], 0
	s_mov_b32 s96, 1.0
	s_mov_b32 s97, 0xbf317218
	s_mov_b32 s98, 0x3db8aa3b
	s_nop 11
	v_pk_add_f32 v[112:113], v[112:113], v[156:157] op_sel_hi:[1,0]
	v_pk_add_f32 v[114:115], v[114:115], v[156:157] op_sel_hi:[1,0]
	v_mul_f32_e64 v234, |v112|, s54
	v_mul_f32_e64 v235, |v113|, s54
	v_mul_f32_e64 v166, |v114|, s54
	v_mul_f32_e64 v167, |v115|, s54
	v_exp_f32_e32 v234, v234
	v_exp_f32_e32 v235, v235
	v_exp_f32_e32 v166, v166
	v_exp_f32_e32 v167, v167
	v_pk_add_f32 v[234:235], v[234:235], s[96:97] op_sel_hi:[1,0]
	v_pk_add_f32 v[166:167], v[166:167], s[96:97] op_sel_hi:[1,0]
	v_log_f32_e32 v234, v234
	v_log_f32_e32 v235, v235
	v_log_f32_e32 v166, v166
	v_log_f32_e32 v167, v167
	v_min_f32_e32 v112, 0, v112
	v_min_f32_e32 v113, 0, v113
	v_min_f32_e32 v114, 0, v114
	v_min_f32_e32 v115, 0, v115
	v_pk_fma_f32 v[112:113], v[234:235], s[96:97], v[112:113] op_sel:[0,1,0] op_sel_hi:[1,1,1]
	v_pk_fma_f32 v[114:115], v[166:167], s[96:97], v[114:115] op_sel:[0,1,0] op_sel_hi:[1,1,1]
	v_pk_mul_f32 v[112:113], v[112:113], s[98:99] op_sel_hi:[1,0]
	v_pk_mul_f32 v[114:115], v[114:115], s[98:99] op_sel_hi:[1,0]
	v_pk_add_f32 v[116:117], v[116:117], v[156:157] op_sel_hi:[1,0]
	v_pk_add_f32 v[118:119], v[118:119], v[156:157] op_sel_hi:[1,0]
	v_mul_f32_e64 v234, |v116|, s54
	v_mul_f32_e64 v235, |v117|, s54
	v_mul_f32_e64 v166, |v118|, s54
	v_mul_f32_e64 v167, |v119|, s54
	v_exp_f32_e32 v234, v234
	v_exp_f32_e32 v235, v235
	v_exp_f32_e32 v166, v166
	v_exp_f32_e32 v167, v167
	v_pk_add_f32 v[234:235], v[234:235], s[96:97] op_sel_hi:[1,0]
	v_pk_add_f32 v[166:167], v[166:167], s[96:97] op_sel_hi:[1,0]
	v_log_f32_e32 v234, v234
	v_log_f32_e32 v235, v235
	v_log_f32_e32 v166, v166
	v_log_f32_e32 v167, v167
	v_min_f32_e32 v116, 0, v116
	v_min_f32_e32 v117, 0, v117
	v_min_f32_e32 v118, 0, v118
	v_min_f32_e32 v119, 0, v119
	v_pk_fma_f32 v[116:117], v[234:235], s[96:97], v[116:117] op_sel:[0,1,0] op_sel_hi:[1,1,1]
	v_pk_fma_f32 v[118:119], v[166:167], s[96:97], v[118:119] op_sel:[0,1,0] op_sel_hi:[1,1,1]
	v_pk_mul_f32 v[116:117], v[116:117], s[98:99] op_sel_hi:[1,0]
	v_pk_mul_f32 v[118:119], v[118:119], s[98:99] op_sel_hi:[1,0]
	v_pk_add_f32 v[120:121], v[120:121], v[156:157] op_sel_hi:[1,0]
	v_pk_add_f32 v[122:123], v[122:123], v[156:157] op_sel_hi:[1,0]
	v_mul_f32_e64 v234, |v120|, s54
	v_mul_f32_e64 v235, |v121|, s54
	v_mul_f32_e64 v166, |v122|, s54
	v_mul_f32_e64 v167, |v123|, s54
	v_exp_f32_e32 v234, v234
	v_exp_f32_e32 v235, v235
	v_exp_f32_e32 v166, v166
	v_exp_f32_e32 v167, v167
	v_pk_add_f32 v[234:235], v[234:235], s[96:97] op_sel_hi:[1,0]
	v_pk_add_f32 v[166:167], v[166:167], s[96:97] op_sel_hi:[1,0]
	v_log_f32_e32 v234, v234
	v_log_f32_e32 v235, v235
	v_log_f32_e32 v166, v166
	v_log_f32_e32 v167, v167
	v_min_f32_e32 v120, 0, v120
	v_min_f32_e32 v121, 0, v121
	v_min_f32_e32 v122, 0, v122
	v_min_f32_e32 v123, 0, v123
	v_pk_fma_f32 v[120:121], v[234:235], s[96:97], v[120:121] op_sel:[0,1,0] op_sel_hi:[1,1,1]
	v_pk_fma_f32 v[122:123], v[166:167], s[96:97], v[122:123] op_sel:[0,1,0] op_sel_hi:[1,1,1]
	v_pk_mul_f32 v[120:121], v[120:121], s[98:99] op_sel_hi:[1,0]
	v_pk_mul_f32 v[122:123], v[122:123], s[98:99] op_sel_hi:[1,0]
	v_pk_add_f32 v[124:125], v[124:125], v[156:157] op_sel_hi:[1,0]
	v_pk_add_f32 v[126:127], v[126:127], v[156:157] op_sel_hi:[1,0]
	v_mul_f32_e64 v234, |v124|, s54
	v_mul_f32_e64 v235, |v125|, s54
	v_mul_f32_e64 v166, |v126|, s54
	v_mul_f32_e64 v167, |v127|, s54
	v_exp_f32_e32 v234, v234
	v_exp_f32_e32 v235, v235
	v_exp_f32_e32 v166, v166
	v_exp_f32_e32 v167, v167
	v_pk_add_f32 v[234:235], v[234:235], s[96:97] op_sel_hi:[1,0]
	v_pk_add_f32 v[166:167], v[166:167], s[96:97] op_sel_hi:[1,0]
	v_log_f32_e32 v234, v234
	v_log_f32_e32 v235, v235
	v_log_f32_e32 v166, v166
	v_log_f32_e32 v167, v167
	v_min_f32_e32 v124, 0, v124
	v_min_f32_e32 v125, 0, v125
	v_min_f32_e32 v126, 0, v126
	v_min_f32_e32 v127, 0, v127
	v_pk_fma_f32 v[124:125], v[234:235], s[96:97], v[124:125] op_sel:[0,1,0] op_sel_hi:[1,1,1]
	v_pk_fma_f32 v[126:127], v[166:167], s[96:97], v[126:127] op_sel:[0,1,0] op_sel_hi:[1,1,1]
	v_pk_mul_f32 v[124:125], v[124:125], s[98:99] op_sel_hi:[1,0]
	v_pk_mul_f32 v[126:127], v[126:127], s[98:99] op_sel_hi:[1,0]
	v_pk_add_f32 v[234:235], v[112:113], v[114:115]
	v_pk_add_f32 v[166:167], v[116:117], v[118:119]
	v_add_f32_e32 v234, v234, v235
	v_add_f32_e32 v166, v166, v167
	ds_write2st64_b32 v169, v234, v166 offset1:4
	v_pk_add_f32 v[234:235], v[120:121], v[122:123]
	v_pk_add_f32 v[166:167], v[124:125], v[126:127]
	v_add_f32_e32 v234, v234, v235
	v_add_f32_e32 v166, v166, v167
	ds_write2st64_b32 v169, v234, v166 offset0:8 offset1:12
	s_branch .LBB0_443
